# attention KV loop: first per-tile workgroup barrier moved ahead of the row-max reduction (the reduction now runs between the two tile barriers)
# speedup vs baseline: 1.0007x; 1.0007x over previous
; __device__ __forceinline__ void partialSM(f32x16& p0, f32x16& p1, float& m_reg, float& mn, float& alpha) {
;     float pmax = p0[0];
; #pragma unroll
;     for (int r = 1; r < 16; ++r) pmax = fmaxf(pmax, p0[r]);
; #pragma unroll
;     for (int r = 0; r < 16; ++r) pmax = fmaxf(pmax, p1[r]);
;     { auto rr = __builtin_amdgcn_permlane32_swap(__float_as_uint(pmax), __float_as_uint(pmax), false, false);
;       pmax = fmaxf(__uint_as_float(rr[0]), __uint_as_float(rr[1])); }
;     if (__builtin_expect(__all((pmax - m_reg) <= THR), 1)) { mn = m_reg; alpha = 1.f; }
;     else { mn = fmaxf(m_reg, pmax); alpha = __builtin_amdgcn_exp2f(m_reg - mn); m_reg = mn; }
.LBB0_528:
	s_barrier
	v_max_f32_e32 v150, v83, v83
	v_max_f32_e32 v151, v82, v82
	v_max_f32_e32 v150, v151, v150
	v_max3_f32 v150, v150, v84, v85
	v_max3_f32 v150, v150, v86, v87
	v_max3_f32 v150, v150, v88, v89
	v_max3_f32 v150, v150, v90, v91
	v_max3_f32 v150, v150, v92, v93
	v_max3_f32 v150, v150, v94, v95
	v_max3_f32 v150, v150, v96, v97
	v_max3_f32 v150, v150, v66, v67
	v_max3_f32 v150, v150, v68, v69
	v_max3_f32 v150, v150, v70, v71
	v_max3_f32 v150, v150, v72, v73
	v_max3_f32 v150, v150, v74, v75
	v_max3_f32 v150, v150, v76, v77
	v_max3_f32 v150, v150, v78, v79
	v_max3_f32 v150, v150, v80, v81
	v_mov_b32_e32 v151, v150
	s_nop 1
	v_permlane32_swap_b32_e32 v150, v151
	v_max_f32_e32 v151, v151, v151
	v_max_f32_e32 v150, v150, v150
	v_max_f32_e32 v150, v150, v151
	v_sub_f32_e32 v151, v150, v162
	v_cmp_ge_f32_e32 vcc, s37, v151
	v_max_f32_e32 v151, v162, v162
	v_max_f32_e32 v150, v151, v150
	v_sub_f32_e32 v151, v162, v150
	v_exp_f32_e32 v151, v151
	s_cmp_eq_u64 vcc, exec
	s_cselect_b64 s[44:45], -1, 0
	s_waitcnt vmcnt(0)
	v_cndmask_b32_e64 v226, v151, 1.0, s[44:45]
	v_cmp_gt_f32_e32 vcc, 1.0, v226
	s_waitcnt vmcnt(4)
	ds_write_b128 v214, v[130:133]
	s_waitcnt vmcnt(3)
	ds_write_b128 v215, v[134:137]
	s_waitcnt vmcnt(2)
	ds_write_b128 v216, v[138:141] offset:32768
	s_waitcnt vmcnt(1)
	ds_write_b128 v216, v[142:145] offset:45056
	s_waitcnt vmcnt(0)
	ds_write_b128 v217, v[146:149] offset:32768
	s_cbranch_vccz .LBB0_532
	s_and_saveexec_b64 s[4:5], s[42:43]
	ds_write_b32 v197, v226 offset:128
	s_or_b64 exec, exec, s[4:5]
	s_waitcnt lgkmcnt(0)
	ds_read_b128 v[152:155], v196 offset:224
	ds_read_b128 v[156:159], v196 offset:192
	ds_read_b128 v[228:231], v196 offset:160
	ds_read_b128 v[232:235], v196 offset:128
	s_waitcnt lgkmcnt(3)
	v_pk_mul_f32 v[64:65], v[64:65], v[154:155]
	s_waitcnt lgkmcnt(2)
	v_pk_mul_f32 v[60:61], v[60:61], v[158:159]
	s_waitcnt lgkmcnt(1)
	v_pk_mul_f32 v[56:57], v[56:57], v[230:231]
	s_waitcnt lgkmcnt(0)
	v_pk_mul_f32 v[52:53], v[52:53], v[234:235]
	v_pk_mul_f32 v[62:63], v[62:63], v[152:153]
	v_pk_mul_f32 v[58:59], v[58:59], v[156:157]
	v_pk_mul_f32 v[54:55], v[54:55], v[228:229]
	v_pk_mul_f32 v[50:51], v[50:51], v[232:233]
	v_pk_mul_f32 v[48:49], v[48:49], v[154:155]
	v_pk_mul_f32 v[44:45], v[44:45], v[158:159]
	v_pk_mul_f32 v[40:41], v[40:41], v[230:231]
	v_pk_mul_f32 v[36:37], v[36:37], v[234:235]
	v_pk_mul_f32 v[46:47], v[46:47], v[152:153]
	v_pk_mul_f32 v[42:43], v[42:43], v[156:157]
	v_pk_mul_f32 v[38:39], v[38:39], v[228:229]
	v_pk_mul_f32 v[34:35], v[34:35], v[232:233]
	v_pk_mul_f32 v[32:33], v[32:33], v[154:155]
	v_pk_mul_f32 v[28:29], v[28:29], v[158:159]
	v_pk_mul_f32 v[24:25], v[24:25], v[230:231]
	v_pk_mul_f32 v[20:21], v[20:21], v[234:235]
	v_pk_mul_f32 v[30:31], v[30:31], v[152:153]
	v_pk_mul_f32 v[26:27], v[26:27], v[156:157]
	v_pk_mul_f32 v[22:23], v[22:23], v[228:229]
	v_pk_mul_f32 v[18:19], v[18:19], v[232:233]
	v_pk_mul_f32 v[16:17], v[16:17], v[154:155]
	v_pk_mul_f32 v[12:13], v[12:13], v[158:159]
	v_pk_mul_f32 v[8:9], v[8:9], v[230:231]
	v_pk_mul_f32 v[4:5], v[4:5], v[234:235]
	v_pk_mul_f32 v[14:15], v[14:15], v[152:153]
	v_pk_mul_f32 v[10:11], v[10:11], v[156:157]
	v_pk_mul_f32 v[6:7], v[6:7], v[228:229]
	v_pk_mul_f32 v[2:3], v[2:3], v[232:233]

; __device__ __forceinline__ void partialSM(f32x16& p0, f32x16& p1, float& m_reg, float& mn, float& alpha) {
;     float pmax = p0[0];
; #pragma unroll
;     for (int r = 1; r < 16; ++r) pmax = fmaxf(pmax, p0[r]);
; #pragma unroll
;     for (int r = 0; r < 16; ++r) pmax = fmaxf(pmax, p1[r]);
;     { auto rr = __builtin_amdgcn_permlane32_swap(__float_as_uint(pmax), __float_as_uint(pmax), false, false);
;       pmax = fmaxf(__uint_as_float(rr[0]), __uint_as_float(rr[1])); }
;     if (__builtin_expect(__all((pmax - m_reg) <= THR), 1)) { mn = m_reg; alpha = 1.f; }
;     else { mn = fmaxf(m_reg, pmax); alpha = __builtin_amdgcn_exp2f(m_reg - mn); m_reg = mn; }
.LBB0_536:
	s_barrier
	v_max_f32_e32 v150, v83, v83
	v_max_f32_e32 v151, v82, v82
	v_max_f32_e32 v150, v151, v150
	v_max3_f32 v150, v150, v84, v85
	v_max3_f32 v150, v150, v86, v87
	v_max3_f32 v150, v150, v88, v89
	v_max3_f32 v150, v150, v90, v91
	v_max3_f32 v150, v150, v92, v93
	v_max3_f32 v150, v150, v94, v95
	v_max3_f32 v150, v150, v96, v97
	v_max3_f32 v150, v150, v66, v67
	v_max3_f32 v150, v150, v68, v69
	v_max3_f32 v150, v150, v70, v71
	v_max3_f32 v150, v150, v72, v73
	v_max3_f32 v150, v150, v74, v75
	v_max3_f32 v150, v150, v76, v77
	v_max3_f32 v150, v150, v78, v79
	v_max3_f32 v150, v150, v80, v81
	v_mov_b32_e32 v151, v150
	s_nop 1
	v_permlane32_swap_b32_e32 v150, v151
	v_max_f32_e32 v151, v151, v151
	v_max_f32_e32 v150, v150, v150
	v_max_f32_e32 v150, v150, v151
	v_sub_f32_e32 v151, v150, v227
	v_cmp_ge_f32_e32 vcc, s37, v151
	s_cmp_eq_u64 vcc, exec
	s_cselect_b64 s[44:45], -1, 0
	s_andn2_b64 vcc, exec, s[16:17]
	s_cbranch_vccnz .LBB0_538
	s_waitcnt vmcnt(0)
	s_waitcnt vmcnt(4)
	ds_write_b128 v214, v[130:133] offset:16384
	s_waitcnt vmcnt(3)
	ds_write_b128 v215, v[134:137] offset:16384
	s_waitcnt vmcnt(2)
	ds_write_b128 v223, v[138:141]
	s_waitcnt vmcnt(1)
	ds_write_b128 v223, v[142:145] offset:12288
	s_waitcnt vmcnt(0)
	ds_write_b128 v217, v[146:149] offset:57344

; __device__ __forceinline__ void partialSM(f32x16& p0, f32x16& p1, float& m_reg, float& mn, float& alpha) {
;     float pmax = p0[0];
; #pragma unroll
;     for (int r = 1; r < 16; ++r) pmax = fmaxf(pmax, p0[r]);
; #pragma unroll
;     for (int r = 0; r < 16; ++r) pmax = fmaxf(pmax, p1[r]);
;     { auto rr = __builtin_amdgcn_permlane32_swap(__float_as_uint(pmax), __float_as_uint(pmax), false, false);
;       pmax = fmaxf(__uint_as_float(rr[0]), __uint_as_float(rr[1])); }
;     if (__builtin_expect(__all((pmax - m_reg) <= THR), 1)) { mn = m_reg; alpha = 1.f; }
;     else { mn = fmaxf(m_reg, pmax); alpha = __builtin_amdgcn_exp2f(m_reg - mn); m_reg = mn; }
.LBB0_697:
	s_barrier
	v_max_f32_e32 v126, v83, v83
	v_max_f32_e32 v127, v82, v82
	v_max_f32_e32 v126, v127, v126
	v_max3_f32 v126, v126, v84, v85
	v_max3_f32 v126, v126, v86, v87
	v_max3_f32 v126, v126, v88, v89
	v_max3_f32 v126, v126, v90, v91
	v_max3_f32 v126, v126, v92, v93
	v_max3_f32 v126, v126, v94, v95
	v_max3_f32 v126, v126, v96, v97
	v_max3_f32 v126, v126, v66, v67
	v_max3_f32 v126, v126, v68, v69
	v_max3_f32 v126, v126, v70, v71
	v_max3_f32 v126, v126, v72, v73
	v_max3_f32 v126, v126, v74, v75
	v_max3_f32 v126, v126, v76, v77
	v_max3_f32 v126, v126, v78, v79
	v_max3_f32 v126, v126, v80, v81
	v_mov_b32_e32 v127, v126
	s_nop 1
	v_permlane32_swap_b32_e32 v126, v127
	v_max_f32_e32 v127, v127, v127
	v_max_f32_e32 v126, v126, v126
	v_max_f32_e32 v126, v126, v127
	v_sub_f32_e32 v127, v126, v130
	v_cmp_ge_f32_e32 vcc, s37, v127
	v_max_f32_e32 v127, v130, v130
	v_max_f32_e32 v126, v127, v126
	v_sub_f32_e32 v127, v130, v126
	v_exp_f32_e32 v127, v127
	s_cmp_eq_u64 vcc, exec
	s_cselect_b64 s[44:45], -1, 0
	s_waitcnt vmcnt(0)
	v_cndmask_b32_e64 v182, v127, 1.0, s[44:45]
	v_cmp_gt_f32_e32 vcc, 1.0, v182
	s_waitcnt vmcnt(2)
	ds_write_b128 v158, v[114:117]
	s_waitcnt vmcnt(1)
	ds_write_b128 v159, v[118:121]
	s_waitcnt vmcnt(0)
	ds_write_b128 v160, v[122:125] offset:32768
	s_cbranch_vccz .LBB0_701
	s_and_saveexec_b64 s[4:5], s[42:43]
	ds_write_b32 v155, v182 offset:128
	s_or_b64 exec, exec, s[4:5]
	s_waitcnt lgkmcnt(0)
	ds_read_b128 v[132:135], v154 offset:224
	ds_read_b128 v[136:139], v154 offset:192
	ds_read_b128 v[184:187], v154 offset:160
	ds_read_b128 v[188:191], v154 offset:128
	s_waitcnt lgkmcnt(3)
	v_pk_mul_f32 v[64:65], v[64:65], v[134:135]
	s_waitcnt lgkmcnt(2)
	v_pk_mul_f32 v[60:61], v[60:61], v[138:139]
	s_waitcnt lgkmcnt(1)
	v_pk_mul_f32 v[56:57], v[56:57], v[186:187]
	s_waitcnt lgkmcnt(0)
	v_pk_mul_f32 v[52:53], v[52:53], v[190:191]
	v_pk_mul_f32 v[62:63], v[62:63], v[132:133]
	v_pk_mul_f32 v[58:59], v[58:59], v[136:137]
	v_pk_mul_f32 v[54:55], v[54:55], v[184:185]
	v_pk_mul_f32 v[50:51], v[50:51], v[188:189]
	v_pk_mul_f32 v[48:49], v[48:49], v[134:135]
	v_pk_mul_f32 v[44:45], v[44:45], v[138:139]
	v_pk_mul_f32 v[40:41], v[40:41], v[186:187]
	v_pk_mul_f32 v[36:37], v[36:37], v[190:191]
	v_pk_mul_f32 v[46:47], v[46:47], v[132:133]
	v_pk_mul_f32 v[42:43], v[42:43], v[136:137]
	v_pk_mul_f32 v[38:39], v[38:39], v[184:185]
	v_pk_mul_f32 v[34:35], v[34:35], v[188:189]
	v_pk_mul_f32 v[32:33], v[32:33], v[134:135]
	v_pk_mul_f32 v[28:29], v[28:29], v[138:139]
	v_pk_mul_f32 v[24:25], v[24:25], v[186:187]
	v_pk_mul_f32 v[20:21], v[20:21], v[190:191]
	v_pk_mul_f32 v[30:31], v[30:31], v[132:133]
	v_pk_mul_f32 v[26:27], v[26:27], v[136:137]
	v_pk_mul_f32 v[22:23], v[22:23], v[184:185]
	v_pk_mul_f32 v[18:19], v[18:19], v[188:189]
	v_pk_mul_f32 v[16:17], v[16:17], v[134:135]
	v_pk_mul_f32 v[12:13], v[12:13], v[138:139]
	v_pk_mul_f32 v[8:9], v[8:9], v[186:187]
	v_pk_mul_f32 v[4:5], v[4:5], v[190:191]
	v_pk_mul_f32 v[14:15], v[14:15], v[132:133]
	v_pk_mul_f32 v[10:11], v[10:11], v[136:137]
	v_pk_mul_f32 v[6:7], v[6:7], v[184:185]
	v_pk_mul_f32 v[2:3], v[2:3], v[188:189]

; __device__ __forceinline__ void partialSM(f32x16& p0, f32x16& p1, float& m_reg, float& mn, float& alpha) {
;     float pmax = p0[0];
; #pragma unroll
;     for (int r = 1; r < 16; ++r) pmax = fmaxf(pmax, p0[r]);
; #pragma unroll
;     for (int r = 0; r < 16; ++r) pmax = fmaxf(pmax, p1[r]);
;     { auto rr = __builtin_amdgcn_permlane32_swap(__float_as_uint(pmax), __float_as_uint(pmax), false, false);
;       pmax = fmaxf(__uint_as_float(rr[0]), __uint_as_float(rr[1])); }
;     if (__builtin_expect(__all((pmax - m_reg) <= THR), 1)) { mn = m_reg; alpha = 1.f; }
;     else { mn = fmaxf(m_reg, pmax); alpha = __builtin_amdgcn_exp2f(m_reg - mn); m_reg = mn; }
.LBB0_707:
	s_barrier
	v_max_f32_e32 v126, v83, v83
	v_max_f32_e32 v127, v82, v82
	v_max_f32_e32 v126, v127, v126
	v_max3_f32 v126, v126, v84, v85
	v_max3_f32 v126, v126, v86, v87
	v_max3_f32 v126, v126, v88, v89
	v_max3_f32 v126, v126, v90, v91
	v_max3_f32 v126, v126, v92, v93
	v_max3_f32 v126, v126, v94, v95
	v_max3_f32 v126, v126, v96, v97
	v_max3_f32 v126, v126, v66, v67
	v_max3_f32 v126, v126, v68, v69
	v_max3_f32 v126, v126, v70, v71
	v_max3_f32 v126, v126, v72, v73
	v_max3_f32 v126, v126, v74, v75
	v_max3_f32 v126, v126, v76, v77
	v_max3_f32 v126, v126, v78, v79
	v_max3_f32 v126, v126, v80, v81
	v_mov_b32_e32 v127, v126
	s_nop 1
	v_permlane32_swap_b32_e32 v126, v127
	v_max_f32_e32 v127, v127, v127
	v_max_f32_e32 v126, v126, v126
	v_max_f32_e32 v126, v126, v127
	v_sub_f32_e32 v127, v126, v183
	v_cmp_ge_f32_e32 vcc, s37, v127
	s_cmp_eq_u64 vcc, exec
	s_cselect_b64 s[44:45], -1, 0
	s_andn2_b64 vcc, exec, s[16:17]
	s_cbranch_vccnz .LBB0_709
	s_waitcnt vmcnt(0)
	s_waitcnt vmcnt(2)
	ds_write_b128 v158, v[114:117] offset:16384
	s_waitcnt vmcnt(1)
	ds_write_b128 v159, v[118:121] offset:16384
	s_waitcnt vmcnt(0)
	ds_write_b128 v160, v[122:125] offset:40960
